# sb attention task: fold canonicalising max into min, interleave the 16 row sum-of-squares reductions in the task epilogue
# baseline (speedup 1.0000x reference)
; __device__ __forceinline__ float ex2(float x) { return __builtin_amdgcn_exp2f(x); }
; __device__ __forceinline__ float lg2(float x) { return __builtin_amdgcn_logf(x); }
; __device__ __forceinline__ int crow(int r, int hi) { return (r & 3) + 8 * (r >> 2) + 4 * hi; }
; #define MFMA32(a, b, c) __builtin_amdgcn_mfma_f32_32x32x16_bf16((a), (b), (c), 0, 0, 0)
; __device__ __forceinline__ void sb_task(int task, const bf16_t* Q, const bf16_t* Kb, const bf16_t* Vt, bf16_t* MIX, float* ss_sb, int lane, bool do_atomic = true) {
;     ...
;     for (int k0 = q0; k0 >= 0; k0 -= 32) {
;         const bf16_t* kp = Kb + (rowbase + k0 + r32) * 512 + h * 64 + hi * 8;
;         bf16x8 kf[4];
; #pragma unroll
;         for (int ks = 0; ks < 4; ++ks) kf[ks] = *(const bf16x8*)(kp + ks * 16);
;         s16x4 vlo[2][2], vhi[2][2];
; #pragma unroll
;         for (int j = 0; j < 2; ++j)
; #pragma unroll
;             for (int db = 0; db < 2; ++db) { const bf16_t* vp = vt + (size_t)(32 * db + r32) * SEQ + k0 + 16 * j + 4 * hi; vlo[j][db] = *(const s16x4*)vp; vhi[j][db] = *(const s16x4*)(vp + 8); }
;         f32x16 s;
; #pragma unroll
;         for (int r = 0; r < 16; ++r) s[r] = 0.f;
; #pragma unroll
;         for (int ks = 0; ks < 4; ++ks) s = MFMA32(kf[ks], qf[ks], s);
;         const bool diag = (k0 == q0);
;         float Lr[16];
; #pragma unroll
;         for (int r = 0; r < 16; ++r) {
;             const float z = s[r];
;             float Lv = fminf(-z, 0.f) - lg2(1.f + ex2(-fabsf(z)));
;             if (diag && crow(r, hi) >= r32) Lv = 0.f;
;             Lr[r] = Lv;
;         }
.LBB0_328:
	s_ashr_i32 s60, s56, 11
	s_ashr_i32 s61, s60, 31
	s_lshl_b32 s58, s56, 5
	s_lshl_b64 s[48:49], s[60:61], 13
	s_and_b32 s58, s58, 0x1fe0
	s_or_b32 s90, s48, s58
	v_mov_b32_e32 v1, s49
	v_or_b32_e32 v0, s90, v80
	s_bfe_u32 s57, s56, 0x30008
	v_lshlrev_b64 v[4:5], 10, v[0:1]
	v_or_b32_e32 v0, s48, v80
	s_lshl_b32 s96, s57, 7
	v_or_b32_e32 v0, s58, v0
	s_waitcnt lgkmcnt(0)
	v_lshl_add_u64 v[2:3], v[84:85], 0, s[96:97]
	v_lshlrev_b64 v[0:1], 10, v[0:1]
	v_lshl_add_u64 v[6:7], v[2:3], 0, v[0:1]
	global_load_dwordx4 v[0:3], v[6:7], off
	v_lshl_add_u64 v[4:5], s[88:89], 0, v[4:5]
	v_lshl_add_u64 v[4:5], v[4:5], 0, s[96:97]
	v_lshl_add_u64 v[28:29], v[82:83], 1, v[4:5]
	global_load_dwordx4 v[48:51], v[28:29], off
	global_load_dwordx4 v[16:19], v[6:7], off offset:32
	global_load_dwordx4 v[52:55], v[28:29], off offset:32
	global_load_dwordx4 v[20:23], v[6:7], off offset:64
	global_load_dwordx4 v[56:59], v[28:29], off offset:64
	global_load_dwordx4 v[24:27], v[6:7], off offset:96
	global_load_dwordx4 v[60:63], v[28:29], off offset:96
	s_lshl_b32 s59, s60, 3
	s_or_b32 s60, s59, s57
	s_ashr_i32 s61, s60, 31
	s_lshl_b64 s[60:61], s[60:61], 20
	s_lshl_b32 s96, s58, 1
	v_mov_b32_e32 v127, v157
	s_mov_b32 s91, s49
	s_waitcnt vmcnt(6)
	v_mfma_f32_32x32x16_bf16 v[0:15], v[0:3], v[48:51], 0
	s_waitcnt vmcnt(4)
	v_mfma_f32_32x32x16_bf16 v[0:15], v[16:19], v[52:55], v[0:15]
	v_lshl_add_u64 v[16:17], v[88:89], 0, s[60:61]
	v_lshl_add_u64 v[16:17], v[16:17], 0, s[96:97]
	v_lshl_add_u64 v[18:19], v[16:17], 0, v[156:157]
	v_lshl_add_u64 v[28:29], v[16:17], 0, v[126:127]
	s_waitcnt vmcnt(2)
	v_mfma_f32_32x32x16_bf16 v[0:15], v[20:23], v[56:59], v[0:15]
	global_load_dwordx2 v[20:21], v[18:19], off
	global_load_dwordx2 v[22:23], v[18:19], off offset:16
	global_load_dwordx2 v[36:37], v[18:19], off offset:32
	global_load_dwordx2 v[38:39], v[18:19], off offset:48
	global_load_dwordx2 v[16:17], v[28:29], off
	s_nop 0
	global_load_dwordx2 v[18:19], v[28:29], off offset:16
	global_load_dwordx2 v[32:33], v[28:29], off offset:32
	global_load_dwordx2 v[34:35], v[28:29], off offset:48
	s_waitcnt vmcnt(8)
	v_mfma_f32_32x32x16_bf16 v[0:15], v[24:27], v[60:63], v[0:15]
	s_nop 11
	v_exp_f32_e64 v25, -|v0|
	v_exp_f32_e64 v30, -|v1|
	v_exp_f32_e64 v31, -|v2|
	v_exp_f32_e64 v40, -|v3|
	v_exp_f32_e64 v43, -|v5|
	v_exp_f32_e64 v45, -|v6|
	v_exp_f32_e64 v47, -|v7|
	v_exp_f32_e64 v67, -|v9|
	v_exp_f32_e64 v69, -|v10|
	v_exp_f32_e64 v41, -|v4|
	v_exp_f32_e64 v65, -|v8|
	v_exp_f32_e64 v71, -|v11|
	v_exp_f32_e64 v73, -|v12|
	v_min_f32_e64 v127, 0, -v4
	v_min_f32_e64 v29, 0, -v9
	v_add_f32_e32 v25, 1.0, v25
	v_add_f32_e32 v30, 1.0, v30
	v_add_f32_e32 v31, 1.0, v31
	v_add_f32_e32 v40, 1.0, v40
	v_add_f32_e32 v43, 1.0, v43
	v_add_f32_e32 v45, 1.0, v45
	v_add_f32_e32 v47, 1.0, v47
	v_add_f32_e32 v66, 1.0, v67
	v_add_f32_e32 v67, 1.0, v69
	v_min_f32_e64 v77, 0, -v1
	v_min_f32_e64 v79, 0, -v3
	v_min_f32_e64 v26, 0, -v5
	v_min_f32_e64 v28, 0, -v6
	v_min_f32_e64 v42, 0, -v7
	v_min_f32_e64 v44, 0, -v10
	v_min_f32_e64 v46, 0, -v11
	v_add_f32_e32 v41, 1.0, v41
	v_add_f32_e32 v65, 1.0, v65
	v_add_f32_e32 v68, 1.0, v71
	v_add_f32_e32 v69, 1.0, v73
	v_log_f32_e32 v25, v25
	v_log_f32_e32 v30, v30
	v_log_f32_e32 v31, v31
	v_log_f32_e32 v70, v40
	v_log_f32_e32 v40, v43
	v_log_f32_e32 v74, v45
	v_log_f32_e32 v43, v47
	v_log_f32_e32 v45, v67
	v_exp_f32_e64 v76, -|v13|
	v_log_f32_e32 v71, v41
	v_log_f32_e32 v41, v65
	v_log_f32_e32 v47, v68
	v_log_f32_e32 v65, v69
	v_min_f32_e64 v24, 0, -v0
	v_min_f32_e64 v78, 0, -v2
	v_min_f32_e64 v27, 0, -v8
	v_min_f32_e64 v64, 0, -v12
	v_sub_f32_e32 v24, v24, v25
	v_sub_f32_e32 v25, v77, v30
	v_sub_f32_e32 v30, v78, v31
	v_sub_f32_e32 v31, v79, v70
	v_sub_f32_e32 v42, v42, v43
	v_sub_f32_e32 v43, v44, v45
	v_sub_f32_e32 v44, v46, v47
	v_sub_f32_e32 v46, v64, v65
	v_cndmask_b32_e64 v65, 0, v31, s[12:13]
	v_cndmask_b32_e64 v31, 0, v43, s[26:27]
	v_add_f32_e32 v43, 1.0, v76
	v_cndmask_b32_e64 v47, 0, v24, s[6:7]
	v_cndmask_b32_e64 v24, 0, v42, s[16:17]
	v_cndmask_b32_e64 v42, 0, v46, s[30:31]
	v_log_f32_e32 v43, v43
	v_exp_f32_e64 v46, -|v14|
	v_cndmask_b32_e64 v45, 0, v44, s[28:29]
	v_min_f32_e64 v44, 0, -v13
	v_sub_f32_e32 v43, v44, v43
	v_add_f32_e32 v44, 1.0, v46
	v_exp_f32_e64 v46, -|v15|
	v_log_f32_e32 v44, v44
	v_log_f32_e32 v75, v66
	v_sub_f32_e32 v66, v127, v71
	v_cndmask_b32_e64 v64, 0, v30, s[10:11]
	v_cndmask_b32_e64 v30, 0, v66, s[14:15]
	v_add_f32_e32 v46, 1.0, v46
	v_min_f32_e64 v66, 0, -v14
	v_log_f32_e32 v46, v46
	v_sub_f32_e32 v44, v66, v44
	v_cndmask_b32_e64 v67, 0, v44, s[36:37]
	v_min_f32_e64 v44, 0, -v15
	v_sub_f32_e32 v44, v44, v46
	v_cndmask_b32_e64 v25, 0, v25, s[8:9]
	v_cndmask_b32_e64 v44, 0, v44, s[38:39]
	v_add_f32_e32 v66, v64, v65
	v_cndmask_b32_e64 v43, 0, v43, s[34:35]
	v_add_f32_e32 v68, v25, v66
	v_add_f32_e32 v46, v67, v44
; __device__ __forceinline__ unsigned cvt_pk_bf16(float lo, float hi) { f32x2 v = {lo, hi}; bf16x2_t b = __builtin_convertvector(v, bf16x2_t); return __builtin_bit_cast(unsigned, b); }
; __device__ __forceinline__ float ex2(float x) { return __builtin_amdgcn_exp2f(x); }
; __device__ __forceinline__ int crow(int r, int hi) { return (r & 3) + 8 * (r >> 2) + 4 * hi; }
; #define MFMA32(a, b, c) __builtin_amdgcn_mfma_f32_32x32x16_bf16((a), (b), (c), 0, 0, 0)
; __device__ __forceinline__ void sb_task(int task, const bf16_t* Q, const bf16_t* Kb, const bf16_t* Vt, bf16_t* MIX, float* ss_sb, int lane, bool do_atomic = true) {
;     ...
;         float tot[4], oth[4], pr[4];
; #pragma unroll
;         for (int G = 0; G < 4; ++G) { Lr[4 * G + 2] += Lr[4 * G + 3]; Lr[4 * G + 1] += Lr[4 * G + 2]; Lr[4 * G] += Lr[4 * G + 1]; tot[G] = Lr[4 * G]; }
; #pragma unroll
;         for (int G = 0; G < 4; ++G) { oth[G] = xshfl<32>(tot[G]); pr[G] = tot[G] + oth[G]; }
;         float off[4];
;         { const float sp3 = 0.f, sp2 = pr[3], sp1 = sp2 + pr[2], sp0 = sp1 + pr[1];
;           off[3] = sp3 + R; off[2] = sp2 + R; off[1] = sp1 + R; off[0] = sp0 + R;
;           if (hi == 0) { off[0] += oth[0]; off[1] += oth[1]; off[2] += oth[2]; off[3] += oth[3]; }
;           R += sp0 + pr[0]; }
;         float w[16];
; #pragma unroll
;         for (int r = 0; r < 16; ++r) { float wv = ex2(s[r] + Lr[r] + off[r >> 2]); if (diag && crow(r, hi) >= r32) wv = 0.f; w[r] = wv; }
;         bf16x8 pa[2];
; #pragma unroll
;         for (int j = 0; j < 2; ++j) { u32x4 p; p.x = cvt_pk_bf16(w[8 * j], w[8 * j + 1]); p.y = cvt_pk_bf16(w[8 * j + 2], w[8 * j + 3]); p.z = cvt_pk_bf16(w[8 * j + 4], w[8 * j + 5]); p.w = cvt_pk_bf16(w[8 * j + 6], w[8 * j + 7]); pa[j] = __builtin_bit_cast(bf16x8, p); }
; #pragma unroll
;         for (int j = 0; j < 2; ++j) {
;             const bf16x8 v0 = (bf16x8){vlo[j][0][0], vlo[j][0][1], vlo[j][0][2], vlo[j][0][3], vhi[j][0][0], vhi[j][0][1], vhi[j][0][2], vhi[j][0][3]};
;             const bf16x8 v1 = (bf16x8){vlo[j][1][0], vlo[j][1][1], vlo[j][1][2], vlo[j][1][3], vhi[j][1][0], vhi[j][1][1], vhi[j][1][2], vhi[j][1][3]};
;             o0 = MFMA32(pa[j], v0, o0); o1 = MFMA32(pa[j], v1, o1);
;         }
;         if (__all(R < -34.f)) break;
	v_add_f32_e32 v69, v47, v68
	v_add_f32_e32 v47, v43, v46
	v_pk_add_f32 v[26:27], v[26:27], v[40:41] neg_lo:[0,1] neg_hi:[0,1]
	v_add_f32_e32 v25, v31, v45
	v_add_f32_e32 v64, v42, v47
	v_mov_b32_e32 v31, v69
	v_mov_b32_e32 v42, v69
	v_cndmask_b32_e64 v41, 0, v27, s[18:19]
	v_cndmask_b32_e64 v40, 0, v26, s[20:21]
	v_pk_add_f32 v[26:27], v[28:29], v[74:75] neg_lo:[0,1] neg_hi:[0,1]
	v_permlane32_swap_b32_e32 v31, v42
	v_cndmask_b32_e64 v27, 0, v27, s[22:23]
	v_cndmask_b32_e64 v26, 0, v26, s[24:25]
	v_cndmask_b32_e64 v70, v31, v42, s[0:1]
	v_mov_b32_e32 v31, v64
	v_mov_b32_e32 v42, v64
	v_pk_add_f32 v[26:27], v[26:27], v[24:25]
	s_nop 0
	v_permlane32_swap_b32_e32 v31, v42
	v_pk_add_f32 v[28:29], v[40:41], v[26:27]
	v_cndmask_b32_e64 v72, v31, v42, s[0:1]
	v_mov_b32_e32 v31, v29
	v_mov_b32_e32 v40, v29
	s_nop 1
	v_permlane32_swap_b32_e32 v31, v40
	v_cndmask_b32_e64 v31, v31, v40, s[0:1]
	v_pk_add_f32 v[40:41], v[30:31], v[28:29]
	v_add_f32_e32 v43, v64, v72
	v_mov_b32_e32 v30, v40
	v_mov_b32_e32 v42, v40
	s_nop 1
	v_permlane32_swap_b32_e32 v30, v42
	v_cndmask_b32_e64 v42, v30, v42, s[0:1]
	v_pk_add_f32 v[74:75], v[40:41], v[42:43]
	v_add_f32_e32 v43, 0, v43
	v_add_f32_e32 v41, v74, v75
	v_add_f32_e32 v67, 0, v75
	v_add_f32_e32 v71, 0, v41
	v_mov_b32_e32 v30, 0
	s_and_saveexec_b64 vcc, s[4:5]
	v_add_f32_e32 v30, 0, v72
	v_add_f32_e32 v43, v43, v31
	v_add_f32_e32 v67, v67, v42
	v_add_f32_e32 v71, v71, v70
	s_or_b64 exec, exec, vcc
	v_add_f32_e32 v0, v0, v69
	v_add_f32_e32 v1, v1, v68
	v_add_f32_e32 v2, v2, v66
	v_add_f32_e32 v3, v3, v65
	v_add_f32_e32 v4, v4, v40
	v_add_f32_e32 v5, v5, v28
	v_add_f32_e32 v6, v6, v26
	v_add_f32_e32 v7, v7, v24
	v_add_f32_e32 v0, v0, v71
	v_add_f32_e32 v1, v1, v71
	v_add_f32_e32 v2, v2, v71
	v_add_f32_e32 v3, v3, v71
	v_add_f32_e32 v4, v4, v67
	v_add_f32_e32 v5, v5, v67
	v_add_f32_e32 v6, v6, v67
	v_add_f32_e32 v7, v7, v67
	v_exp_f32_e32 v0, v0
	v_exp_f32_e32 v1, v1
	v_exp_f32_e32 v2, v2
	v_exp_f32_e32 v3, v3
	v_exp_f32_e32 v4, v4
	v_exp_f32_e32 v5, v5
	v_exp_f32_e32 v6, v6
	v_exp_f32_e32 v7, v7
	v_add_f32_e32 v8, v8, v29
	v_add_f32_e32 v9, v9, v27
	v_add_f32_e32 v10, v10, v25
	v_add_f32_e32 v11, v11, v45
	v_add_f32_e32 v12, v12, v64
	v_add_f32_e32 v13, v13, v47
	v_add_f32_e32 v14, v14, v46
	v_add_f32_e32 v15, v15, v44
	v_cndmask_b32_e64 v0, 0, v0, s[6:7]
	v_cndmask_b32_e64 v1, 0, v1, s[8:9]
	v_cndmask_b32_e64 v2, 0, v2, s[10:11]
	v_cndmask_b32_e64 v3, 0, v3, s[12:13]
	v_cndmask_b32_e64 v4, 0, v4, s[14:15]
	v_cndmask_b32_e64 v5, 0, v5, s[20:21]
	v_cndmask_b32_e64 v6, 0, v6, s[24:25]
	v_cndmask_b32_e64 v7, 0, v7, s[16:17]
	v_add_f32_e32 v8, v8, v43
	v_add_f32_e32 v9, v9, v43
	v_add_f32_e32 v10, v10, v43
	v_add_f32_e32 v11, v11, v43
	v_add_f32_e32 v12, v12, v30
	v_add_f32_e32 v13, v13, v30
	v_add_f32_e32 v14, v14, v30
	v_add_f32_e32 v15, v15, v30
	v_exp_f32_e32 v8, v8
	v_exp_f32_e32 v9, v9
	v_exp_f32_e32 v10, v10
	v_exp_f32_e32 v11, v11
	v_exp_f32_e32 v12, v12
	v_exp_f32_e32 v13, v13
	v_exp_f32_e32 v14, v14
	v_exp_f32_e32 v15, v15
	v_cvt_pk_bf16_f32 v24, v0, v1
	v_cvt_pk_bf16_f32 v25, v2, v3
	v_cvt_pk_bf16_f32 v26, v4, v5
	v_cvt_pk_bf16_f32 v27, v6, v7
	v_add_f32_e32 v31, v69, v70
	v_cndmask_b32_e64 v8, 0, v8, s[18:19]
	v_cndmask_b32_e64 v9, 0, v9, s[22:23]
	v_cndmask_b32_e64 v10, 0, v10, s[26:27]
	v_cndmask_b32_e64 v11, 0, v11, s[28:29]
	v_cndmask_b32_e64 v12, 0, v12, s[30:31]
	v_cndmask_b32_e64 v13, 0, v13, s[34:35]
	v_cndmask_b32_e64 v14, 0, v14, s[36:37]
	v_cndmask_b32_e64 v15, 0, v15, s[38:39]
	v_add_f32_e32 v41, v31, v41
	v_cvt_pk_bf16_f32 v42, v8, v9
	v_cvt_pk_bf16_f32 v43, v10, v11
	v_cvt_pk_bf16_f32 v44, v12, v13
	v_cvt_pk_bf16_f32 v45, v14, v15
	s_waitcnt vmcnt(6)
	v_mfma_f32_32x32x16_bf16 v[0:15], v[24:27], v[20:23], 0
	v_cmp_gt_f32_e32 vcc, s87, v41
	s_cmp_eq_u64 vcc, exec
	s_cselect_b64 s[60:61], -1, 0
	s_cmp_eq_u32 s58, 0
	s_cselect_b64 s[62:63], -1, 0
	s_or_b64 s[60:61], s[62:63], s[60:61]
	s_and_b64 vcc, exec, s[60:61]
	s_waitcnt vmcnt(2)
	v_mfma_f32_32x32x16_bf16 v[16:31], v[24:27], v[16:19], 0
	v_mfma_f32_32x32x16_bf16 v[0:15], v[42:45], v[36:39], v[0:15]
	s_waitcnt vmcnt(0)
	v_mfma_f32_32x32x16_bf16 v[16:31], v[42:45], v[32:35], v[16:31]
	s_cbranch_vccnz .LBB0_335
	s_lshr_b32 s60, s56, 8
	s_and_b32 vcc_lo, s60, 7
	s_and_b32 s60, s55, 0x1fe0
	s_lshl_b32 s62, vcc_lo, 7
	s_add_i32 vcc_lo, s59, vcc_lo
	s_sub_i32 s96, s60, 32
	s_ashr_i32 vcc_hi, vcc_lo, 31
	s_lshl_b64 s[60:61], s[96:97], 1
	s_lshl_b64 vcc, vcc, 20
	s_add_u32 s60, s60, vcc_lo
	s_addc_u32 s61, s61, vcc_hi
	s_add_u32 s48, s96, s48
	s_addc_u32 s49, 0, s49
	v_lshl_add_u64 v[32:33], s[48:49], 0, v[80:81]
	v_lshlrev_b64 v[32:33], 10, v[32:33]
	s_mov_b32 s63, s97
	v_lshl_add_u64 v[32:33], v[124:125], 0, v[32:33]
	v_add_f32_e32 v127, 0, v41
	v_lshl_add_u64 v[128:129], s[60:61], 0, v[122:123]
	v_lshl_add_u64 v[130:131], v[32:33], 0, s[62:63]
	s_branch .LBB0_333

; __device__ __forceinline__ float ex2(float x) { return __builtin_amdgcn_exp2f(x); }
; __device__ __forceinline__ float lg2(float x) { return __builtin_amdgcn_logf(x); }
; __device__ __forceinline__ int crow(int r, int hi) { return (r & 3) + 8 * (r >> 2) + 4 * hi; }
; #define MFMA32(a, b, c) __builtin_amdgcn_mfma_f32_32x32x16_bf16((a), (b), (c), 0, 0, 0)
; __device__ __forceinline__ void sb_task(int task, const bf16_t* Q, const bf16_t* Kb, const bf16_t* Vt, bf16_t* MIX, float* ss_sb, int lane, bool do_atomic = true) {
;     ...
;     for (int k0 = q0; k0 >= 0; k0 -= 32) {
;         const bf16_t* kp = Kb + (rowbase + k0 + r32) * 512 + h * 64 + hi * 8;
;         bf16x8 kf[4];
; #pragma unroll
;         for (int ks = 0; ks < 4; ++ks) kf[ks] = *(const bf16x8*)(kp + ks * 16);
;         s16x4 vlo[2][2], vhi[2][2];
; #pragma unroll
;         for (int j = 0; j < 2; ++j)
; #pragma unroll
;             for (int db = 0; db < 2; ++db) { const bf16_t* vp = vt + (size_t)(32 * db + r32) * SEQ + k0 + 16 * j + 4 * hi; vlo[j][db] = *(const s16x4*)vp; vhi[j][db] = *(const s16x4*)(vp + 8); }
;         f32x16 s;
; #pragma unroll
;         for (int r = 0; r < 16; ++r) s[r] = 0.f;
; #pragma unroll
;         for (int ks = 0; ks < 4; ++ks) s = MFMA32(kf[ks], qf[ks], s);
;         const bool diag = (k0 == q0);
;         float Lr[16];
; #pragma unroll
;         for (int r = 0; r < 16; ++r) {
;             const float z = s[r];
;             float Lv = fminf(-z, 0.f) - lg2(1.f + ex2(-fabsf(z)));
;             if (diag && crow(r, hi) >= r32) Lv = 0.f;
;             Lr[r] = Lv;
;         }
.LBB0_333:
	v_lshl_add_u64 v[36:37], s[42:43], 0, v[130:131]
	global_load_dwordx4 v[32:35], v[36:37], off offset:-64
	global_load_dwordx4 v[132:135], v[36:37], off offset:-32
	global_load_dwordx4 v[136:139], v[36:37], off
	global_load_dwordx4 v[140:143], v[36:37], off offset:32
	v_lshl_add_u64 v[36:37], s[42:43], 0, v[128:129]
	v_add_co_u32_e32 v38, vcc, 0x8000000, v36
	s_nop 1
	v_addc_co_u32_e32 v39, vcc, 0, v37, vcc
	v_add_co_u32_e32 v36, vcc, 0x8080000, v36
	global_load_dwordx2 v[76:77], v[38:39], off
	global_load_dwordx2 v[78:79], v[38:39], off offset:16
	v_addc_co_u32_e32 v37, vcc, 0, v37, vcc
	global_load_dwordx2 v[72:73], v[36:37], off
	global_load_dwordx2 v[74:75], v[36:37], off offset:16
	global_load_dwordx2 v[68:69], v[38:39], off offset:32
	global_load_dwordx2 v[70:71], v[38:39], off offset:48
	global_load_dwordx2 v[64:65], v[36:37], off offset:32
	global_load_dwordx2 v[66:67], v[36:37], off offset:48
	s_waitcnt vmcnt(11)
	v_mfma_f32_32x32x16_bf16 v[32:47], v[32:35], v[48:51], 0
	s_waitcnt vmcnt(10)
	v_mfma_f32_32x32x16_bf16 v[32:47], v[132:135], v[52:55], v[32:47]
	s_waitcnt vmcnt(9)
	v_mfma_f32_32x32x16_bf16 v[32:47], v[136:139], v[56:59], v[32:47]
	s_waitcnt vmcnt(8)
	v_mfma_f32_32x32x16_bf16 v[32:47], v[140:143], v[60:63], v[32:47]
	s_nop 11
	v_exp_f32_e64 v133, -|v32|
	v_min_f32_e64 v132, 0, -v32
	v_exp_f32_e64 v135, -|v39|
	v_add_f32_e32 v133, 1.0, v133
	v_log_f32_e32 v133, v133
	v_exp_f32_e64 v147, -|v46|
	v_add_f32_e32 v135, 1.0, v135
	v_log_f32_e32 v137, v135
	v_sub_f32_e32 v134, v132, v133
	v_exp_f32_e64 v133, -|v33|
	v_min_f32_e64 v132, 0, -v33
	v_add_f32_e32 v133, 1.0, v133
	v_log_f32_e32 v133, v133
	v_exp_f32_e64 v149, -|v47|
	v_exp_f32_e64 v138, -|v44|
	v_exp_f32_e64 v142, -|v45|
	v_sub_f32_e32 v144, v132, v133
	v_exp_f32_e64 v133, -|v34|
	v_min_f32_e64 v132, 0, -v34
	v_add_f32_e32 v147, 1.0, v147
	v_add_f32_e32 v133, 1.0, v133
	v_log_f32_e32 v133, v133
	v_add_f32_e32 v149, 1.0, v149
	v_log_f32_e32 v148, v147
	v_log_f32_e32 v149, v149
	v_sub_f32_e32 v150, v132, v133
	v_exp_f32_e64 v133, -|v35|
	v_min_f32_e64 v132, 0, -v35
	v_add_f32_e32 v133, 1.0, v133
	v_log_f32_e32 v133, v133
	v_add_f32_e32 v138, 1.0, v138
	v_add_f32_e32 v142, 1.0, v142
	v_sub_f32_e32 v152, v132, v133
	v_exp_f32_e64 v133, -|v36|
	v_min_f32_e64 v132, 0, -v36
	v_add_f32_e32 v155, v150, v152
	v_add_f32_e32 v133, 1.0, v133
	v_log_f32_e32 v133, v133
	v_add_f32_e32 v166, v144, v155
	v_add_f32_e32 v153, v134, v166
	v_min_f32_e64 v146, 0, -v46
	v_sub_f32_e32 v151, v132, v133
	v_exp_f32_e64 v133, -|v37|
	v_min_f32_e64 v132, 0, -v37
	v_min_f32_e64 v147, 0, -v47
	v_add_f32_e32 v133, 1.0, v133
	v_log_f32_e32 v133, v133
	v_mov_b32_e32 v134, v153
	v_log_f32_e32 v138, v138
	v_log_f32_e32 v142, v142
	v_sub_f32_e32 v158, v132, v133
	v_exp_f32_e64 v133, -|v38|
	v_min_f32_e64 v132, 0, -v38
	v_pk_add_f32 v[146:147], v[146:147], v[148:149] neg_lo:[0,1] neg_hi:[0,1]
	v_add_f32_e32 v133, 1.0, v133
	v_log_f32_e32 v136, v133
	v_min_f32_e64 v133, 0, -v39
	v_pk_add_f32 v[132:133], v[132:133], v[136:137] neg_lo:[0,1] neg_hi:[0,1]
	v_min_f32_e64 v137, 0, -v40
	v_exp_f32_e64 v135, -|v40|
	v_exp_f32_e64 v136, -|v42|
	v_add_f32_e32 v154, v132, v133
	v_add_f32_e32 v167, v158, v154
	v_add_f32_e32 v135, 1.0, v135
	v_log_f32_e32 v139, v135
	v_min_f32_e64 v141, 0, -v41
	v_exp_f32_e64 v135, -|v41|
	v_add_f32_e32 v136, 1.0, v136
	v_log_f32_e32 v136, v136
	v_mov_b32_e32 v132, v153
	v_add_f32_e32 v135, 1.0, v135
	v_log_f32_e32 v143, v135
	v_min_f32_e64 v135, 0, -v42
	v_sub_f32_e32 v145, v135, v136
	v_exp_f32_e64 v136, -|v43|
	v_add_f32_e32 v148, v151, v167
	v_permlane32_swap_b32_e32 v132, v134
	v_add_f32_e32 v136, 1.0, v136
	v_log_f32_e32 v136, v136
	v_min_f32_e64 v135, 0, -v43
	v_cndmask_b32_e64 v132, v132, v134, s[0:1]
	v_mov_b32_e32 v134, v148
	v_mov_b32_e32 v144, v148
	v_sub_f32_e32 v135, v135, v136
	v_permlane32_swap_b32_e32 v134, v144
	v_min_f32_e64 v136, 0, -v44
	v_min_f32_e64 v140, 0, -v45
	v_cndmask_b32_e64 v150, v134, v144, s[0:1]
	v_mov_b32_e32 v144, v146
	v_mov_b32_e32 v134, v147
	v_pk_add_f32 v[168:169], v[136:137], v[138:139] neg_lo:[0,1] neg_hi:[0,1]
	v_pk_add_f32 v[138:139], v[140:141], v[142:143] neg_lo:[0,1] neg_hi:[0,1]
	v_pk_add_f32 v[136:137], v[144:145], v[134:135]
	s_nop 0
	v_pk_add_f32 v[138:139], v[138:139], v[136:137]
	s_nop 0
	v_pk_add_f32 v[140:141], v[168:169], v[138:139]
	s_nop 0
	v_mov_b32_e32 v134, v141
	v_mov_b32_e32 v142, v141
	v_mov_b32_e32 v144, v140
	v_mov_b32_e32 v145, v140
	v_permlane32_swap_b32_e32 v134, v142
	s_nop 0
	v_permlane32_swap_b32_e32 v144, v145
	v_cndmask_b32_e64 v143, v134, v142, s[0:1]
	v_cndmask_b32_e64 v142, v144, v145, s[0:1]
	v_pk_add_f32 v[168:169], v[140:141], v[142:143]
	v_add_f32_e32 v144, 0, v127
	v_mov_b32_e32 v149, v168
	v_mov_b32_e32 v151, v169
	v_pk_add_f32 v[170:171], v[148:149], v[150:151]
	v_add_f32_e32 v145, v127, v168
	v_add_f32_e32 v134, v170, v171
	v_add_f32_e32 v146, v127, v171
	v_add_f32_e32 v149, v127, v134
	s_and_saveexec_b64 s[48:49], s[4:5]
	s_cbranch_execz .LBB0_332
	v_add_f32_e32 v144, v144, v142
	v_add_f32_e32 v145, v145, v143
	v_add_f32_e32 v146, v146, v150
	v_add_f32_e32 v149, v149, v132
	s_branch .LBB0_332
; __device__ __forceinline__ bf16_t f2bf(float f) { unsigned u = __builtin_bit_cast(unsigned, f); return (bf16_t)((u + 0x7fffu + ((u >> 16) & 1u)) >> 16); }
; __device__ __forceinline__ int crow(int r, int hi) { return (r & 3) + 8 * (r >> 2) + 4 * hi; }
; __device__ __forceinline__ void sb_task(int task, const bf16_t* Q, const bf16_t* Kb, const bf16_t* Vt, bf16_t* MIX, float* ss_sb, int lane, bool do_atomic = true) {
;     ...
; #pragma unroll
;     for (int r = 0; r < 16; ++r) {
;         const size_t row = rowbase + q0 + crow(r, hi);
;         MIX[row * 1024 + h * 64 + r32] = f2bf(o0[r]);
;         MIX[row * 1024 + h * 64 + 32 + r32] = f2bf(o1[r]);
;         float ss = o0[r] * o0[r] + o1[r] * o1[r];
;         ss += xshfl<1>(ss); ss += xshfl<2>(ss); ss += xshfl<4>(ss); ss += xshfl<8>(ss); ss += xshfl<16>(ss);
;         if (r32 == 0 && do_atomic) atomicAdd(ss_sb + row, ss);
;     }
.LBB0_335:
	s_lshl_b32 s48, s57, 6
	s_lshl_b32 s96, s48, 1
	v_lshl_add_u64 v[34:35], s[90:91], 0, v[86:87]
	s_nop 5
	s_nop 7
	v_lshl_add_u64 v[32:33], v[120:121], 0, s[96:97]
	v_lshl_add_u64 v[34:35], s[90:91], 0, v[86:87]
	v_bfe_u32 v38, v0, 16, 1
	v_add3_u32 v38, v0, v38, s52
	v_lshlrev_b64 v[36:37], 11, v[34:35]
	v_lshl_add_u64 v[36:37], v[32:33], 0, v[36:37]
	v_bfe_u32 v39, v16, 16, 1
	v_add3_u32 v39, v16, v39, s52
	global_store_short_d16_hi v[36:37], v38, off
	global_store_short_d16_hi v[36:37], v39, off offset:64
	v_mul_f32_e32 v48, v16, v16
	v_fmac_f32_e32 v48, v0, v0
	v_lshl_add_u64 v[34:35], s[90:91], 0, v[90:91]
	v_bfe_u32 v42, v1, 16, 1
	v_add3_u32 v42, v1, v42, s52
	v_lshlrev_b64 v[40:41], 11, v[34:35]
	v_lshl_add_u64 v[40:41], v[32:33], 0, v[40:41]
	v_bfe_u32 v43, v17, 16, 1
	v_add3_u32 v43, v17, v43, s52
	global_store_short_d16_hi v[40:41], v42, off
	global_store_short_d16_hi v[40:41], v43, off offset:64
	v_mul_f32_e32 v49, v17, v17
	v_fmac_f32_e32 v49, v1, v1
	v_lshl_add_u64 v[34:35], s[90:91], 0, v[92:93]
	v_bfe_u32 v46, v2, 16, 1
	v_add3_u32 v46, v2, v46, s52
	v_lshlrev_b64 v[44:45], 11, v[34:35]
	v_lshl_add_u64 v[44:45], v[32:33], 0, v[44:45]
	v_bfe_u32 v47, v18, 16, 1
	v_add3_u32 v47, v18, v47, s52
	global_store_short_d16_hi v[44:45], v46, off
	global_store_short_d16_hi v[44:45], v47, off offset:64
	v_mul_f32_e32 v50, v18, v18
	v_fmac_f32_e32 v50, v2, v2
	v_lshl_add_u64 v[34:35], s[90:91], 0, v[94:95]
	v_bfe_u32 v38, v3, 16, 1
	v_add3_u32 v38, v3, v38, s52
	v_lshlrev_b64 v[36:37], 11, v[34:35]
	v_lshl_add_u64 v[36:37], v[32:33], 0, v[36:37]
	v_bfe_u32 v39, v19, 16, 1
	v_add3_u32 v39, v19, v39, s52
	global_store_short_d16_hi v[36:37], v38, off
	global_store_short_d16_hi v[36:37], v39, off offset:64
	v_mul_f32_e32 v51, v19, v19
	v_fmac_f32_e32 v51, v3, v3
	v_lshl_add_u64 v[34:35], s[90:91], 0, v[96:97]
	v_bfe_u32 v42, v4, 16, 1
	v_add3_u32 v42, v4, v42, s52
	v_lshlrev_b64 v[40:41], 11, v[34:35]
	v_lshl_add_u64 v[40:41], v[32:33], 0, v[40:41]
	v_bfe_u32 v43, v20, 16, 1
	v_add3_u32 v43, v20, v43, s52
	global_store_short_d16_hi v[40:41], v42, off
	global_store_short_d16_hi v[40:41], v43, off offset:64
	v_mul_f32_e32 v52, v20, v20
	v_fmac_f32_e32 v52, v4, v4
	v_lshl_add_u64 v[34:35], s[90:91], 0, v[100:101]
	v_bfe_u32 v46, v5, 16, 1
	v_add3_u32 v46, v5, v46, s52
	v_lshlrev_b64 v[44:45], 11, v[34:35]
	v_lshl_add_u64 v[44:45], v[32:33], 0, v[44:45]
	v_bfe_u32 v47, v21, 16, 1
	v_add3_u32 v47, v21, v47, s52
	global_store_short_d16_hi v[44:45], v46, off
	global_store_short_d16_hi v[44:45], v47, off offset:64
	v_mul_f32_e32 v53, v21, v21
	v_fmac_f32_e32 v53, v5, v5
	v_lshl_add_u64 v[34:35], s[90:91], 0, v[104:105]
	v_bfe_u32 v38, v6, 16, 1
	v_add3_u32 v38, v6, v38, s52
	v_lshlrev_b64 v[36:37], 11, v[34:35]
	v_lshl_add_u64 v[36:37], v[32:33], 0, v[36:37]
	v_bfe_u32 v39, v22, 16, 1
	v_add3_u32 v39, v22, v39, s52
	global_store_short_d16_hi v[36:37], v38, off
	global_store_short_d16_hi v[36:37], v39, off offset:64
	v_mul_f32_e32 v54, v22, v22
	v_fmac_f32_e32 v54, v6, v6
	v_lshl_add_u64 v[34:35], s[90:91], 0, v[98:99]
	v_bfe_u32 v42, v7, 16, 1
	v_add3_u32 v42, v7, v42, s52
	v_lshlrev_b64 v[40:41], 11, v[34:35]
	v_lshl_add_u64 v[40:41], v[32:33], 0, v[40:41]
	v_bfe_u32 v43, v23, 16, 1
	v_add3_u32 v43, v23, v43, s52
	global_store_short_d16_hi v[40:41], v42, off
	global_store_short_d16_hi v[40:41], v43, off offset:64
	v_mul_f32_e32 v55, v23, v23
	v_fmac_f32_e32 v55, v7, v7
	v_lshl_add_u64 v[34:35], s[90:91], 0, v[102:103]
	v_bfe_u32 v46, v8, 16, 1
	v_add3_u32 v46, v8, v46, s52
	v_lshlrev_b64 v[44:45], 11, v[34:35]
	v_lshl_add_u64 v[44:45], v[32:33], 0, v[44:45]
	v_bfe_u32 v47, v24, 16, 1
	v_add3_u32 v47, v24, v47, s52
	global_store_short_d16_hi v[44:45], v46, off
	global_store_short_d16_hi v[44:45], v47, off offset:64
	v_mul_f32_e32 v56, v24, v24
	v_fmac_f32_e32 v56, v8, v8
	v_lshl_add_u64 v[34:35], s[90:91], 0, v[106:107]
	v_bfe_u32 v38, v9, 16, 1
	v_add3_u32 v38, v9, v38, s52
	v_lshlrev_b64 v[36:37], 11, v[34:35]
	v_lshl_add_u64 v[36:37], v[32:33], 0, v[36:37]
	v_bfe_u32 v39, v25, 16, 1
	v_add3_u32 v39, v25, v39, s52
	global_store_short_d16_hi v[36:37], v38, off
	global_store_short_d16_hi v[36:37], v39, off offset:64
	v_mul_f32_e32 v57, v25, v25
	v_fmac_f32_e32 v57, v9, v9
	v_lshl_add_u64 v[34:35], s[90:91], 0, v[108:109]
	v_bfe_u32 v42, v10, 16, 1
	v_add3_u32 v42, v10, v42, s52
	v_lshlrev_b64 v[40:41], 11, v[34:35]
	v_lshl_add_u64 v[40:41], v[32:33], 0, v[40:41]
	v_bfe_u32 v43, v26, 16, 1
	v_add3_u32 v43, v26, v43, s52
	global_store_short_d16_hi v[40:41], v42, off
	global_store_short_d16_hi v[40:41], v43, off offset:64
	v_mul_f32_e32 v58, v26, v26
	v_fmac_f32_e32 v58, v10, v10
	v_lshl_add_u64 v[34:35], s[90:91], 0, v[110:111]
	v_bfe_u32 v46, v11, 16, 1
	v_add3_u32 v46, v11, v46, s52
	v_lshlrev_b64 v[44:45], 11, v[34:35]
	v_lshl_add_u64 v[44:45], v[32:33], 0, v[44:45]
	v_bfe_u32 v47, v27, 16, 1
	v_add3_u32 v47, v27, v47, s52
	global_store_short_d16_hi v[44:45], v46, off
	global_store_short_d16_hi v[44:45], v47, off offset:64
	v_mul_f32_e32 v59, v27, v27
	v_fmac_f32_e32 v59, v11, v11
	v_lshl_add_u64 v[34:35], s[90:91], 0, v[112:113]
	v_bfe_u32 v38, v12, 16, 1
	v_add3_u32 v38, v12, v38, s52
	v_lshlrev_b64 v[36:37], 11, v[34:35]
	v_lshl_add_u64 v[36:37], v[32:33], 0, v[36:37]
	v_bfe_u32 v39, v28, 16, 1
	v_add3_u32 v39, v28, v39, s52
	global_store_short_d16_hi v[36:37], v38, off
	global_store_short_d16_hi v[36:37], v39, off offset:64
	v_mul_f32_e32 v60, v28, v28
	v_fmac_f32_e32 v60, v12, v12
	v_lshl_add_u64 v[34:35], s[90:91], 0, v[114:115]
	v_bfe_u32 v42, v13, 16, 1
	v_add3_u32 v42, v13, v42, s52
	v_lshlrev_b64 v[40:41], 11, v[34:35]
; __device__ __forceinline__ bf16_t f2bf(float f) { unsigned u = __builtin_bit_cast(unsigned, f); return (bf16_t)((u + 0x7fffu + ((u >> 16) & 1u)) >> 16); }
; __device__ __forceinline__ int crow(int r, int hi) { return (r & 3) + 8 * (r >> 2) + 4 * hi; }
; __device__ __forceinline__ void sb_task(int task, const bf16_t* Q, const bf16_t* Kb, const bf16_t* Vt, bf16_t* MIX, float* ss_sb, int lane, bool do_atomic = true) {
;     ...
;     for (int r = 0; r < 16; ++r) {
;         const size_t row = rowbase + q0 + crow(r, hi);
;         MIX[row * 1024 + h * 64 + r32] = f2bf(o0[r]);
;         MIX[row * 1024 + h * 64 + 32 + r32] = f2bf(o1[r]);
;         float ss = o0[r] * o0[r] + o1[r] * o1[r];
;         ss += xshfl<1>(ss); ss += xshfl<2>(ss); ss += xshfl<4>(ss); ss += xshfl<8>(ss); ss += xshfl<16>(ss);
	v_lshl_add_u64 v[40:41], v[32:33], 0, v[40:41]
	v_bfe_u32 v43, v29, 16, 1
	v_add3_u32 v43, v29, v43, s52
	global_store_short_d16_hi v[40:41], v42, off
	global_store_short_d16_hi v[40:41], v43, off offset:64
	v_mul_f32_e32 v61, v29, v29
	v_fmac_f32_e32 v61, v13, v13
	v_lshl_add_u64 v[34:35], s[90:91], 0, v[116:117]
	v_bfe_u32 v46, v14, 16, 1
	v_add3_u32 v46, v14, v46, s52
	v_lshlrev_b64 v[44:45], 11, v[34:35]
	v_lshl_add_u64 v[44:45], v[32:33], 0, v[44:45]
	v_bfe_u32 v47, v30, 16, 1
	v_add3_u32 v47, v30, v47, s52
	global_store_short_d16_hi v[44:45], v46, off
	global_store_short_d16_hi v[44:45], v47, off offset:64
	v_mul_f32_e32 v62, v30, v30
	v_fmac_f32_e32 v62, v14, v14
	v_lshl_add_u64 v[34:35], s[90:91], 0, v[118:119]
	v_bfe_u32 v38, v15, 16, 1
	v_add3_u32 v38, v15, v38, s52
	v_lshlrev_b64 v[36:37], 11, v[34:35]
	v_lshl_add_u64 v[36:37], v[32:33], 0, v[36:37]
	v_bfe_u32 v39, v31, 16, 1
	v_add3_u32 v39, v31, v39, s52
	global_store_short_d16_hi v[36:37], v38, off
	global_store_short_d16_hi v[36:37], v39, off offset:64
	v_mul_f32_e32 v63, v31, v31
	v_fmac_f32_e32 v63, v15, v15
	ds_swizzle_b32 v64, v48 offset:swizzle(SWAP,1)
	ds_swizzle_b32 v65, v49 offset:swizzle(SWAP,1)
	ds_swizzle_b32 v66, v50 offset:swizzle(SWAP,1)
	ds_swizzle_b32 v67, v51 offset:swizzle(SWAP,1)
	ds_swizzle_b32 v68, v52 offset:swizzle(SWAP,1)
	ds_swizzle_b32 v69, v53 offset:swizzle(SWAP,1)
	ds_swizzle_b32 v70, v54 offset:swizzle(SWAP,1)
	ds_swizzle_b32 v71, v55 offset:swizzle(SWAP,1)
	ds_swizzle_b32 v72, v56 offset:swizzle(SWAP,1)
	s_waitcnt lgkmcnt(8)
	v_add_f32_e32 v48, v48, v64
	ds_swizzle_b32 v73, v57 offset:swizzle(SWAP,1)
	s_waitcnt lgkmcnt(8)
	v_add_f32_e32 v49, v49, v65
	ds_swizzle_b32 v74, v58 offset:swizzle(SWAP,1)
	s_waitcnt lgkmcnt(8)
	v_add_f32_e32 v50, v50, v66
	ds_swizzle_b32 v75, v59 offset:swizzle(SWAP,1)
	s_waitcnt lgkmcnt(8)
	v_add_f32_e32 v51, v51, v67
	ds_swizzle_b32 v76, v60 offset:swizzle(SWAP,1)
	s_waitcnt lgkmcnt(8)
	v_add_f32_e32 v52, v52, v68
	ds_swizzle_b32 v77, v61 offset:swizzle(SWAP,1)
	s_waitcnt lgkmcnt(8)
	v_add_f32_e32 v53, v53, v69
	ds_swizzle_b32 v78, v62 offset:swizzle(SWAP,1)
	s_waitcnt lgkmcnt(8)
	v_add_f32_e32 v54, v54, v70
	ds_swizzle_b32 v79, v63 offset:swizzle(SWAP,1)
	s_waitcnt lgkmcnt(8)
	v_add_f32_e32 v55, v55, v71
	s_waitcnt lgkmcnt(7)
	v_add_f32_e32 v56, v56, v72
	s_waitcnt lgkmcnt(6)
	v_add_f32_e32 v57, v57, v73
	s_waitcnt lgkmcnt(5)
	v_add_f32_e32 v58, v58, v74
	s_waitcnt lgkmcnt(4)
	v_add_f32_e32 v59, v59, v75
	s_waitcnt lgkmcnt(3)
	v_add_f32_e32 v60, v60, v76
	s_waitcnt lgkmcnt(2)
	v_add_f32_e32 v61, v61, v77
	s_waitcnt lgkmcnt(1)
	v_add_f32_e32 v62, v62, v78
	s_waitcnt lgkmcnt(0)
	v_add_f32_e32 v63, v63, v79
	ds_swizzle_b32 v64, v48 offset:swizzle(SWAP,2)
	ds_swizzle_b32 v65, v49 offset:swizzle(SWAP,2)
	ds_swizzle_b32 v66, v50 offset:swizzle(SWAP,2)
	ds_swizzle_b32 v67, v51 offset:swizzle(SWAP,2)
	ds_swizzle_b32 v68, v52 offset:swizzle(SWAP,2)
	ds_swizzle_b32 v69, v53 offset:swizzle(SWAP,2)
	ds_swizzle_b32 v70, v54 offset:swizzle(SWAP,2)
	ds_swizzle_b32 v71, v55 offset:swizzle(SWAP,2)
	ds_swizzle_b32 v72, v56 offset:swizzle(SWAP,2)
	s_waitcnt lgkmcnt(8)
	v_add_f32_e32 v48, v48, v64
	ds_swizzle_b32 v73, v57 offset:swizzle(SWAP,2)
	s_waitcnt lgkmcnt(8)
	v_add_f32_e32 v49, v49, v65
	ds_swizzle_b32 v74, v58 offset:swizzle(SWAP,2)
	s_waitcnt lgkmcnt(8)
	v_add_f32_e32 v50, v50, v66
	ds_swizzle_b32 v75, v59 offset:swizzle(SWAP,2)
	s_waitcnt lgkmcnt(8)
	v_add_f32_e32 v51, v51, v67
	ds_swizzle_b32 v76, v60 offset:swizzle(SWAP,2)
	s_waitcnt lgkmcnt(8)
	v_add_f32_e32 v52, v52, v68
	ds_swizzle_b32 v77, v61 offset:swizzle(SWAP,2)
	s_waitcnt lgkmcnt(8)
	v_add_f32_e32 v53, v53, v69
	ds_swizzle_b32 v78, v62 offset:swizzle(SWAP,2)
	s_waitcnt lgkmcnt(8)
	v_add_f32_e32 v54, v54, v70
	ds_swizzle_b32 v79, v63 offset:swizzle(SWAP,2)
	s_waitcnt lgkmcnt(8)
	v_add_f32_e32 v55, v55, v71
	s_waitcnt lgkmcnt(7)
	v_add_f32_e32 v56, v56, v72
	s_waitcnt lgkmcnt(6)
	v_add_f32_e32 v57, v57, v73
	s_waitcnt lgkmcnt(5)
	v_add_f32_e32 v58, v58, v74
	s_waitcnt lgkmcnt(4)
	v_add_f32_e32 v59, v59, v75
	s_waitcnt lgkmcnt(3)
	v_add_f32_e32 v60, v60, v76
	s_waitcnt lgkmcnt(2)
	v_add_f32_e32 v61, v61, v77
	s_waitcnt lgkmcnt(1)
	v_add_f32_e32 v62, v62, v78
	s_waitcnt lgkmcnt(0)
	v_add_f32_e32 v63, v63, v79
	ds_swizzle_b32 v64, v48 offset:swizzle(SWAP,4)
	ds_swizzle_b32 v65, v49 offset:swizzle(SWAP,4)
	ds_swizzle_b32 v66, v50 offset:swizzle(SWAP,4)
	ds_swizzle_b32 v67, v51 offset:swizzle(SWAP,4)
	ds_swizzle_b32 v68, v52 offset:swizzle(SWAP,4)
	ds_swizzle_b32 v69, v53 offset:swizzle(SWAP,4)
	ds_swizzle_b32 v70, v54 offset:swizzle(SWAP,4)
	ds_swizzle_b32 v71, v55 offset:swizzle(SWAP,4)
	ds_swizzle_b32 v72, v56 offset:swizzle(SWAP,4)
	s_waitcnt lgkmcnt(8)
	v_add_f32_e32 v48, v48, v64
	ds_swizzle_b32 v73, v57 offset:swizzle(SWAP,4)
	s_waitcnt lgkmcnt(8)
	v_add_f32_e32 v49, v49, v65
	ds_swizzle_b32 v74, v58 offset:swizzle(SWAP,4)
	s_waitcnt lgkmcnt(8)
	v_add_f32_e32 v50, v50, v66
	ds_swizzle_b32 v75, v59 offset:swizzle(SWAP,4)
	s_waitcnt lgkmcnt(8)
	v_add_f32_e32 v51, v51, v67
	ds_swizzle_b32 v76, v60 offset:swizzle(SWAP,4)
	s_waitcnt lgkmcnt(8)
	v_add_f32_e32 v52, v52, v68
	ds_swizzle_b32 v77, v61 offset:swizzle(SWAP,4)
	s_waitcnt lgkmcnt(8)
	v_add_f32_e32 v53, v53, v69
	ds_swizzle_b32 v78, v62 offset:swizzle(SWAP,4)
	s_waitcnt lgkmcnt(8)
	v_add_f32_e32 v54, v54, v70
	ds_swizzle_b32 v79, v63 offset:swizzle(SWAP,4)
	s_waitcnt lgkmcnt(8)
	v_add_f32_e32 v55, v55, v71
	s_waitcnt lgkmcnt(7)
	v_add_f32_e32 v56, v56, v72
	s_waitcnt lgkmcnt(6)
	v_add_f32_e32 v57, v57, v73
	s_waitcnt lgkmcnt(5)
	v_add_f32_e32 v58, v58, v74
	s_waitcnt lgkmcnt(4)
	v_add_f32_e32 v59, v59, v75
	s_waitcnt lgkmcnt(3)
; __device__ __forceinline__ void sb_task(int task, const bf16_t* Q, const bf16_t* Kb, const bf16_t* Vt, bf16_t* MIX, float* ss_sb, int lane, bool do_atomic = true) {
;     ...
;         float ss = o0[r] * o0[r] + o1[r] * o1[r];
;         ss += xshfl<1>(ss); ss += xshfl<2>(ss); ss += xshfl<4>(ss); ss += xshfl<8>(ss); ss += xshfl<16>(ss);
;         if (r32 == 0 && do_atomic) atomicAdd(ss_sb + row, ss);
	v_add_f32_e32 v60, v60, v76
	s_waitcnt lgkmcnt(2)
	v_add_f32_e32 v61, v61, v77
	s_waitcnt lgkmcnt(1)
	v_add_f32_e32 v62, v62, v78
	s_waitcnt lgkmcnt(0)
	v_add_f32_e32 v63, v63, v79
	ds_swizzle_b32 v64, v48 offset:swizzle(SWAP,8)
	ds_swizzle_b32 v65, v49 offset:swizzle(SWAP,8)
	ds_swizzle_b32 v66, v50 offset:swizzle(SWAP,8)
	ds_swizzle_b32 v67, v51 offset:swizzle(SWAP,8)
	ds_swizzle_b32 v68, v52 offset:swizzle(SWAP,8)
	ds_swizzle_b32 v69, v53 offset:swizzle(SWAP,8)
	ds_swizzle_b32 v70, v54 offset:swizzle(SWAP,8)
	ds_swizzle_b32 v71, v55 offset:swizzle(SWAP,8)
	ds_swizzle_b32 v72, v56 offset:swizzle(SWAP,8)
	s_waitcnt lgkmcnt(8)
	v_add_f32_e32 v48, v48, v64
	ds_swizzle_b32 v73, v57 offset:swizzle(SWAP,8)
	s_waitcnt lgkmcnt(8)
	v_add_f32_e32 v49, v49, v65
	ds_swizzle_b32 v74, v58 offset:swizzle(SWAP,8)
	s_waitcnt lgkmcnt(8)
	v_add_f32_e32 v50, v50, v66
	ds_swizzle_b32 v75, v59 offset:swizzle(SWAP,8)
	s_waitcnt lgkmcnt(8)
	v_add_f32_e32 v51, v51, v67
	ds_swizzle_b32 v76, v60 offset:swizzle(SWAP,8)
	s_waitcnt lgkmcnt(8)
	v_add_f32_e32 v52, v52, v68
	ds_swizzle_b32 v77, v61 offset:swizzle(SWAP,8)
	s_waitcnt lgkmcnt(8)
	v_add_f32_e32 v53, v53, v69
	ds_swizzle_b32 v78, v62 offset:swizzle(SWAP,8)
	s_waitcnt lgkmcnt(8)
	v_add_f32_e32 v54, v54, v70
	ds_swizzle_b32 v79, v63 offset:swizzle(SWAP,8)
	s_waitcnt lgkmcnt(8)
	v_add_f32_e32 v55, v55, v71
	s_waitcnt lgkmcnt(7)
	v_add_f32_e32 v56, v56, v72
	s_waitcnt lgkmcnt(6)
	v_add_f32_e32 v57, v57, v73
	s_waitcnt lgkmcnt(5)
	v_add_f32_e32 v58, v58, v74
	s_waitcnt lgkmcnt(4)
	v_add_f32_e32 v59, v59, v75
	s_waitcnt lgkmcnt(3)
	v_add_f32_e32 v60, v60, v76
	s_waitcnt lgkmcnt(2)
	v_add_f32_e32 v61, v61, v77
	s_waitcnt lgkmcnt(1)
	v_add_f32_e32 v62, v62, v78
	s_waitcnt lgkmcnt(0)
	v_add_f32_e32 v63, v63, v79
	ds_swizzle_b32 v64, v48 offset:swizzle(SWAP,16)
	ds_swizzle_b32 v65, v49 offset:swizzle(SWAP,16)
	ds_swizzle_b32 v66, v50 offset:swizzle(SWAP,16)
	ds_swizzle_b32 v67, v51 offset:swizzle(SWAP,16)
	ds_swizzle_b32 v68, v52 offset:swizzle(SWAP,16)
	ds_swizzle_b32 v69, v53 offset:swizzle(SWAP,16)
	ds_swizzle_b32 v70, v54 offset:swizzle(SWAP,16)
	ds_swizzle_b32 v71, v55 offset:swizzle(SWAP,16)
	ds_swizzle_b32 v72, v56 offset:swizzle(SWAP,16)
	s_waitcnt lgkmcnt(8)
	v_add_f32_e32 v48, v48, v64
	ds_swizzle_b32 v73, v57 offset:swizzle(SWAP,16)
	s_waitcnt lgkmcnt(8)
	v_add_f32_e32 v49, v49, v65
	ds_swizzle_b32 v74, v58 offset:swizzle(SWAP,16)
	s_waitcnt lgkmcnt(8)
	v_add_f32_e32 v50, v50, v66
	ds_swizzle_b32 v75, v59 offset:swizzle(SWAP,16)
	s_waitcnt lgkmcnt(8)
	v_add_f32_e32 v51, v51, v67
	ds_swizzle_b32 v76, v60 offset:swizzle(SWAP,16)
	s_waitcnt lgkmcnt(8)
	v_add_f32_e32 v52, v52, v68
	ds_swizzle_b32 v77, v61 offset:swizzle(SWAP,16)
	s_waitcnt lgkmcnt(8)
	v_add_f32_e32 v53, v53, v69
	ds_swizzle_b32 v78, v62 offset:swizzle(SWAP,16)
	s_waitcnt lgkmcnt(8)
	v_add_f32_e32 v54, v54, v70
	ds_swizzle_b32 v79, v63 offset:swizzle(SWAP,16)
	s_waitcnt lgkmcnt(8)
	v_add_f32_e32 v55, v55, v71
	s_waitcnt lgkmcnt(7)
	v_add_f32_e32 v56, v56, v72
	s_waitcnt lgkmcnt(6)
	v_add_f32_e32 v57, v57, v73
	s_waitcnt lgkmcnt(5)
	v_add_f32_e32 v58, v58, v74
	s_waitcnt lgkmcnt(4)
	v_add_f32_e32 v59, v59, v75
	s_waitcnt lgkmcnt(3)
	v_add_f32_e32 v60, v60, v76
	s_waitcnt lgkmcnt(2)
	v_add_f32_e32 v61, v61, v77
	s_waitcnt lgkmcnt(1)
	v_add_f32_e32 v62, v62, v78
	s_waitcnt lgkmcnt(0)
	v_add_f32_e32 v63, v63, v79
	s_and_saveexec_b64 s[48:49], s[40:41]
	s_cbranch_execz .LBB0_327
	v_lshl_add_u64 v[34:35], s[90:91], 0, v[86:87]
	v_lshl_add_u64 v[34:35], v[34:35], 2, s[46:47]
	global_atomic_add_f32 v[34:35], v48, off
	v_lshl_add_u64 v[34:35], s[90:91], 0, v[90:91]
	v_lshl_add_u64 v[34:35], v[34:35], 2, s[46:47]
	global_atomic_add_f32 v[34:35], v49, off
	v_lshl_add_u64 v[34:35], s[90:91], 0, v[92:93]
	v_lshl_add_u64 v[34:35], v[34:35], 2, s[46:47]
	global_atomic_add_f32 v[34:35], v50, off
	v_lshl_add_u64 v[34:35], s[90:91], 0, v[94:95]
	v_lshl_add_u64 v[34:35], v[34:35], 2, s[46:47]
	global_atomic_add_f32 v[34:35], v51, off
	v_lshl_add_u64 v[34:35], s[90:91], 0, v[96:97]
	v_lshl_add_u64 v[34:35], v[34:35], 2, s[46:47]
	global_atomic_add_f32 v[34:35], v52, off
	v_lshl_add_u64 v[34:35], s[90:91], 0, v[100:101]
	v_lshl_add_u64 v[34:35], v[34:35], 2, s[46:47]
	global_atomic_add_f32 v[34:35], v53, off
	v_lshl_add_u64 v[34:35], s[90:91], 0, v[104:105]
	v_lshl_add_u64 v[34:35], v[34:35], 2, s[46:47]
	global_atomic_add_f32 v[34:35], v54, off
	v_lshl_add_u64 v[34:35], s[90:91], 0, v[98:99]
	v_lshl_add_u64 v[34:35], v[34:35], 2, s[46:47]
	global_atomic_add_f32 v[34:35], v55, off
	v_lshl_add_u64 v[34:35], s[90:91], 0, v[102:103]
	v_lshl_add_u64 v[34:35], v[34:35], 2, s[46:47]
	global_atomic_add_f32 v[34:35], v56, off
	v_lshl_add_u64 v[34:35], s[90:91], 0, v[106:107]
	v_lshl_add_u64 v[34:35], v[34:35], 2, s[46:47]
	global_atomic_add_f32 v[34:35], v57, off
	v_lshl_add_u64 v[34:35], s[90:91], 0, v[108:109]
	v_lshl_add_u64 v[34:35], v[34:35], 2, s[46:47]
	global_atomic_add_f32 v[34:35], v58, off
	v_lshl_add_u64 v[34:35], s[90:91], 0, v[110:111]
	v_lshl_add_u64 v[34:35], v[34:35], 2, s[46:47]
	global_atomic_add_f32 v[34:35], v59, off
	v_lshl_add_u64 v[34:35], s[90:91], 0, v[112:113]
	v_lshl_add_u64 v[34:35], v[34:35], 2, s[46:47]
	global_atomic_add_f32 v[34:35], v60, off
	v_lshl_add_u64 v[34:35], s[90:91], 0, v[114:115]
	v_lshl_add_u64 v[34:35], v[34:35], 2, s[46:47]
	global_atomic_add_f32 v[34:35], v61, off
	v_lshl_add_u64 v[34:35], s[90:91], 0, v[116:117]
	v_lshl_add_u64 v[34:35], v[34:35], 2, s[46:47]
	global_atomic_add_f32 v[34:35], v62, off
	v_lshl_add_u64 v[34:35], s[90:91], 0, v[118:119]
	v_lshl_add_u64 v[34:35], v[34:35], 2, s[46:47]
	global_atomic_add_f32 v[34:35], v63, off
	s_branch .LBB0_327
